# attention V tile keys permuted within 16-key groups so V fragment reads are ds_read_b128 instead of ds_read2_b64
# speedup vs baseline: 1.0219x; 1.0051x over previous
; __device__ __forceinline__ int mk_tid() { int t = threadIdx.x; asm volatile("" : "+v"(t)); return t; }
; #define LAS __attribute__((address_space(3)))
; __device__ __forceinline__ void dattn_unit(LAS unsigned char* lds, int b, int h, int qb, const bf16* Q, const bf16* K, const bf16* V, bf16* YB, float lam, const float* subg, float oml, int tid) {
;     tid = mk_tid();
;     const int lane = tid & 63, w = __builtin_amdgcn_readfirstlane(tid >> 6), ql = lane & 31, hi = lane >> 5;
;     const LAS float* tab = (const LAS float*)(lds + AT_TAB);
;     const size_t rowb = (size_t)b * SEQ;
;     const int qmin = qb * 256 + w * 32, q = qmin + ql, qmax = qmin + 31;
;     LAS bf16x8* qs = (LAS bf16x8*)(lds + AT_QS) + w * 512 + lane;
; #pragma unroll
;     for (int mp = 0; mp < 2; ++mp)
; #pragma unroll
;         for (int ks = 0; ks < 4; ++ks) qs[(mp * 4 + ks) * 64] = *(const bf16x8*)(Q + (rowb + q) * 1024 + h * 128 + mp * 64 + ks * 16 + hi * 8);
;     f32x16 o[2][4];
; #pragma unroll
;     for (int mp = 0; mp < 2; ++mp)
; #pragma unroll
;         for (int cb = 0; cb < 4; ++cb) o[mp][cb] = f32x16{};
;     float mref[2] = {0.f, 0.f}, lsum[2] = {0.f, 0.f};
;     const int NT = 4 * qb + 4;
;     const bf16* kg = K + (rowb + (tid >> 3)) * 1024 + h * 128 + (tid & 7) * 8;
;     const bf16* vg = V + (rowb + (tid & 63)) * 1024 + h * 128 + (tid >> 6) * 16;
;     v4u kr0 = *(const v4u*)(kg), kr1 = *(const v4u*)(kg + 64), vr0 = *(const v4u*)(vg), vr1 = *(const v4u*)(vg + 8);
;     ...
;     AT_STAGE(0);
;     __syncthreads();
.LBB0_225:
	v_mov_b32_e32 v54, v211
	s_lshl_b32 s19, s35, 8
	v_ashrrev_i32_e32 v52, 6, v54
	v_ashrrev_i32_e32 v48, 3, v54
	v_readfirstlane_b32 s18, v52
	s_lshl_b32 s31, s18, 5
	v_ashrrev_i32_e32 v49, 31, v48
	v_and_b32_e32 v55, 31, v54
	s_add_i32 s31, s31, s19
	v_lshl_add_u64 v[32:33], s[6:7], 0, v[48:49]
	v_lshlrev_b32_e32 v34, 3, v54
	v_or_b32_e32 v178, s31, v55
	v_lshlrev_b64 v[32:33], 11, v[32:33]
	v_and_b32_e32 v34, 56, v34
	v_and_b32_e32 v53, 63, v54
	v_ashrrev_i32_e32 v179, 31, v178
	v_lshl_add_u64 v[32:33], s[10:11], 0, v[32:33]
	v_lshlrev_b32_e32 v180, 1, v34
	v_mov_b32_e32 v181, v209
	v_lshl_add_u64 v[0:1], s[6:7], 0, v[178:179]
	v_lshl_add_u64 v[36:37], v[32:33], 0, v[180:181]
	v_or_b32_e32 v32, s6, v53
	v_mov_b32_e32 v33, s7
	v_lshlrev_b32_e32 v34, 4, v52
	v_bfe_u32 v194, v54, 5, 1
	v_lshlrev_b64 v[0:1], 11, v[0:1]
	v_lshlrev_b64 v[32:33], 11, v[32:33]
	v_ashrrev_i32_e32 v35, 31, v34
	v_lshl_add_u64 v[176:177], s[8:9], 0, v[0:1]
	v_lshlrev_b32_e32 v208, 4, v194
	v_lshl_add_u64 v[32:33], s[20:21], 0, v[32:33]
	v_lshlrev_b64 v[50:51], 1, v[34:35]
	v_lshl_add_u64 v[28:29], v[176:177], 0, v[208:209]
	v_lshl_add_u64 v[44:45], v[32:33], 0, v[50:51]
	global_load_dwordx4 v[0:3], v[28:29], off
	global_load_dwordx4 v[4:7], v[28:29], off offset:32
	global_load_dwordx4 v[8:11], v[28:29], off offset:64
	global_load_dwordx4 v[12:15], v[28:29], off offset:96
	global_load_dwordx4 v[16:19], v[28:29], off offset:128
	global_load_dwordx4 v[20:23], v[28:29], off offset:160
	global_load_dwordx4 v[24:27], v[28:29], off offset:192
	s_nop 0
	global_load_dwordx4 v[28:31], v[28:29], off offset:224
	s_nop 0
	global_load_dwordx4 v[32:35], v[36:37], off
	s_nop 0
	global_load_dwordx4 v[36:39], v[36:37], off offset:128
	s_nop 0
	global_load_dwordx4 v[40:43], v[44:45], off
	s_nop 0
	global_load_dwordx4 v[44:47], v[44:45], off offset:16
	s_lshl_b32 s19, s35, 10
	s_or_b32 s56, s19, 0x300
	s_movk_i32 s19, 0x48
	s_lshl_b32 s18, s18, 13
	v_mul_lo_u32 v56, v48, s19
	s_movk_i32 s19, 0x480
	s_add_i32 s18, s18, 0
	v_mul_lo_u32 v57, v52, s19
	v_lshlrev_b32_e32 v195, 1, v53
	v_lshrrev_b32_e32 v58, 2, v53
	v_lshrrev_b32_e32 v59, 3, v53
	v_xor_b32_e32 v58, v58, v59
	v_and_b32_e32 v58, 1, v58
	v_mul_u32_u24_e32 v58, 24, v58
	v_xor_b32_e32 v195, v195, v58
	v_lshlrev_b32_e32 v52, 11, v53
	v_lshl_add_u32 v53, v53, 4, s18
	v_lshlrev_b32_e32 v196, 1, v56
	v_lshlrev_b32_e32 v197, 1, v57
	v_add_u32_e32 v189, 0x12400, v53
	v_mov_b32_e32 v53, v209
	v_mul_u32_u24_e32 v192, 0x90, v55
	v_add3_u32 v55, 0, v196, v180
	v_add3_u32 v56, 0, v197, v195
	v_lshlrev_b32_e32 v193, 4, v194
	s_or_b32 s35, s31, 31
	s_mov_b32 s57, 0
	v_mov_b32_e32 v179, 0
	s_movk_i32 s58, 0xb0
	v_mov_b32_e32 v181, 0
	v_mov_b32_e32 v190, 0
	v_mov_b32_e32 v191, 0
	s_mov_b32 s59, 0
	s_waitcnt vmcnt(11)
	ds_write_b128 v189, v[0:3]
	s_waitcnt vmcnt(10)
	ds_write_b128 v189, v[4:7] offset:1024
	s_waitcnt vmcnt(9)
	ds_write_b128 v189, v[8:11] offset:2048
	s_waitcnt vmcnt(8)
	ds_write_b128 v189, v[12:15] offset:3072
	s_waitcnt vmcnt(7)
	ds_write_b128 v189, v[16:19] offset:4096
	s_waitcnt vmcnt(6)
	ds_write_b128 v189, v[20:23] offset:5120
	s_waitcnt vmcnt(5)
	ds_write_b128 v189, v[24:27] offset:6144
	s_waitcnt vmcnt(4)
	ds_write_b128 v189, v[28:31] offset:7168
	s_waitcnt vmcnt(3)
	ds_write_b128 v55, v[32:35]
	s_waitcnt vmcnt(2)
	ds_write_b128 v55, v[36:39] offset:9216
	s_waitcnt vmcnt(1)
	ds_write_b16 v56, v40 offset:18432
	ds_write_b16_d16_hi v56, v40 offset:18576
	ds_write_b16 v56, v41 offset:18720
	ds_write_b16_d16_hi v56, v41 offset:18864
	ds_write_b16 v56, v42 offset:19008
	ds_write_b16_d16_hi v56, v42 offset:19152
	ds_write_b16 v56, v43 offset:19296
	ds_write_b16_d16_hi v56, v43 offset:19440
	s_waitcnt vmcnt(0)
	ds_write_b16 v56, v44 offset:19584
	ds_write_b16_d16_hi v56, v44 offset:19728
	ds_write_b16 v56, v45 offset:19872
	ds_write_b16_d16_hi v56, v45 offset:20016
	ds_write_b16 v56, v46 offset:20160
	ds_write_b16_d16_hi v56, v46 offset:20304
	ds_write_b16 v56, v47 offset:20448
	ds_write_b16_d16_hi v56, v47 offset:20592
	v_lshl_add_u64 v[0:1], v[52:53], 0, v[50:51]
	v_lshl_add_u64 v[182:183], s[44:45], 0, v[0:1]
	v_lshlrev_b64 v[0:1], 11, v[48:49]
	v_and_b32_e32 v2, 7, v54
	v_lshl_or_b32 v0, v2, 4, v0
	v_lshl_add_u64 v[184:185], s[44:45], 0, v[0:1]
	v_lshlrev_b32_e32 v0, 2, v178
	v_sub_u32_e32 v0, v208, v0
	v_mov_b32_e32 v14, v209
	v_mov_b32_e32 v15, v209
	v_add_u32_e32 v198, 0, v0
	v_mov_b32_e32 v0, v209
	v_mov_b32_e32 v1, v209
	v_mov_b32_e32 v2, v209
	v_mov_b32_e32 v3, v209
	v_mov_b32_e32 v4, v209
	v_mov_b32_e32 v5, v209
	v_mov_b32_e32 v6, v209
	v_mov_b32_e32 v7, v209
	v_mov_b32_e32 v8, v209
	v_mov_b32_e32 v9, v209
	v_mov_b32_e32 v10, v209
	v_mov_b32_e32 v11, v209
	v_mov_b32_e32 v12, v209
	v_mov_b32_e32 v13, v209
	v_mov_b64_e32 v[46:47], v[14:15]
	v_mov_b64_e32 v[78:79], v[14:15]
	v_mov_b64_e32 v[110:111], v[14:15]
	v_mov_b64_e32 v[30:31], v[14:15]
	v_mov_b64_e32 v[62:63], v[14:15]
	v_mov_b64_e32 v[94:95], v[14:15]
	v_mov_b64_e32 v[126:127], v[14:15]
	v_mov_b64_e32 v[44:45], v[12:13]
	v_mov_b64_e32 v[42:43], v[10:11]
	v_mov_b64_e32 v[40:41], v[8:9]
	v_mov_b64_e32 v[38:39], v[6:7]
	v_mov_b64_e32 v[36:37], v[4:5]
	v_mov_b64_e32 v[34:35], v[2:3]
	v_mov_b64_e32 v[32:33], v[0:1]
	v_mov_b64_e32 v[76:77], v[12:13]
	v_mov_b64_e32 v[74:75], v[10:11]
	v_mov_b64_e32 v[72:73], v[8:9]
	v_mov_b64_e32 v[70:71], v[6:7]
	v_mov_b64_e32 v[68:69], v[4:5]
	v_mov_b64_e32 v[66:67], v[2:3]
	v_mov_b64_e32 v[64:65], v[0:1]
	v_mov_b64_e32 v[108:109], v[12:13]
	v_mov_b64_e32 v[106:107], v[10:11]
	v_mov_b64_e32 v[104:105], v[8:9]
	v_mov_b64_e32 v[102:103], v[6:7]
	v_mov_b64_e32 v[100:101], v[4:5]
	v_mov_b64_e32 v[98:99], v[2:3]
	v_mov_b64_e32 v[96:97], v[0:1]
	v_mov_b64_e32 v[28:29], v[12:13]
	v_mov_b64_e32 v[26:27], v[10:11]
	v_mov_b64_e32 v[24:25], v[8:9]
	v_mov_b64_e32 v[22:23], v[6:7]
	v_mov_b64_e32 v[20:21], v[4:5]
	v_mov_b64_e32 v[18:19], v[2:3]
	v_mov_b64_e32 v[16:17], v[0:1]
	v_mov_b64_e32 v[60:61], v[12:13]
	v_mov_b64_e32 v[58:59], v[10:11]
	v_mov_b64_e32 v[56:57], v[8:9]
	v_mov_b64_e32 v[54:55], v[6:7]
	v_mov_b64_e32 v[52:53], v[4:5]
	v_mov_b64_e32 v[50:51], v[2:3]
	v_mov_b64_e32 v[48:49], v[0:1]
	v_mov_b64_e32 v[92:93], v[12:13]
	v_mov_b64_e32 v[90:91], v[10:11]
	v_mov_b64_e32 v[88:89], v[8:9]
	v_mov_b64_e32 v[86:87], v[6:7]
	v_mov_b64_e32 v[84:85], v[4:5]
	v_mov_b64_e32 v[82:83], v[2:3]
	v_mov_b64_e32 v[80:81], v[0:1]
	v_mov_b64_e32 v[124:125], v[12:13]
	v_mov_b64_e32 v[122:123], v[10:11]
	v_mov_b64_e32 v[120:121], v[8:9]
	v_mov_b64_e32 v[118:119], v[6:7]
	v_mov_b64_e32 v[116:117], v[4:5]
	v_mov_b64_e32 v[114:115], v[2:3]
	v_mov_b64_e32 v[112:113], v[0:1]
	s_waitcnt lgkmcnt(0)
	s_barrier
	s_branch .LBB0_227

; #define LAS __attribute__((address_space(3)))
; __device__ __forceinline__ void dattn_unit(LAS unsigned char* lds, int b, int h, int qb, const bf16* Q, const bf16* K, const bf16* V, bf16* YB, float lam, const float* subg, float oml, int tid) {
;     ...
;             AT_SOFTMAX(s0, 0, pA0, pB0);
;             AT_SOFTMAX(s1, 1, pA1, pB1);
; #pragma unroll
;             for (int cb = 0; cb < 4; ++cb) { const LAS bf16* vp = Vt + (32 * cb + ql) * 72 + 32 * sub + 4 * hi;
;                 const v2u a0 = *(const LAS v2u*)(vp), a1 = *(const LAS v2u*)(vp + 8), a2 = *(const LAS v2u*)(vp + 16), a3 = *(const LAS v2u*)(vp + 24);
;                 const v4u f0 = {a0.x, a0.y, a1.x, a1.y}, f1 = {a2.x, a2.y, a3.x, a3.y};
;                 o[0][cb] = __builtin_amdgcn_mfma_f32_32x32x16_bf16(__builtin_bit_cast(bf16x8, f0), pA0, o[0][cb], 0, 0, 0);
;                 o[1][cb] = __builtin_amdgcn_mfma_f32_32x32x16_bf16(__builtin_bit_cast(bf16x8, f0), pA1, o[1][cb], 0, 0, 0);
;                 o[0][cb] = __builtin_amdgcn_mfma_f32_32x32x16_bf16(__builtin_bit_cast(bf16x8, f1), pB0, o[0][cb], 0, 0, 0);
;                 o[1][cb] = __builtin_amdgcn_mfma_f32_32x32x16_bf16(__builtin_bit_cast(bf16x8, f1), pB1, o[1][cb], 0, 0, 0); }
.LBB0_230:
	v_add_u32_e32 v219, s38, v193
	v_add_u32_e32 v219, v219, v192
	v_add_u32_e32 v224, 0x5800, v219
	v_add_u32_e32 v200, 0x7800, v219
	ds_read_b128 v[228:231], v224 offset:512
	ds_read_b128 v[232:235], v224 offset:544
	v_add_u32_e32 v224, 0x6800, v219
	ds_read_b128 v[236:239], v224 offset:1024
	ds_read_b128 v[240:243], v224 offset:1056
	ds_read_b128 v[212:215], v200 offset:1536
	v_add_u32_e32 v219, 0x4800, v219
	ds_read_b128 v[220:223], v219
	v_exp_f32_e32 v201, v144
	v_exp_f32_e32 v202, v145
	v_exp_f32_e32 v203, v146
	v_exp_f32_e32 v204, v147
	v_add_f32_e32 v144, 0, v201
	v_exp_f32_e32 v205, v148
	v_add_f32_e32 v144, v202, v144
	v_exp_f32_e32 v206, v149
	v_add_f32_e32 v144, v203, v144
	v_exp_f32_e32 v207, v150
	v_add_f32_e32 v144, v204, v144
	v_exp_f32_e32 v218, v151
	v_add_f32_e32 v144, v205, v144
	v_exp_f32_e32 v147, v152
	v_add_f32_e32 v144, v206, v144
	v_exp_f32_e32 v148, v153
	v_add_f32_e32 v144, v207, v144
	v_exp_f32_e32 v149, v154
	v_add_f32_e32 v144, v218, v144
	v_exp_f32_e32 v150, v155
	v_add_f32_e32 v144, v147, v144
	v_exp_f32_e32 v151, v156
	v_add_f32_e32 v144, v148, v144
	v_exp_f32_e32 v152, v157
	v_add_f32_e32 v144, v149, v144
	v_exp_f32_e32 v153, v158
	v_add_f32_e32 v144, v150, v144
	v_exp_f32_e32 v154, v159
	v_add_f32_e32 v144, v151, v144
	v_add_f32_e32 v144, v152, v144
	v_add_f32_e32 v144, v153, v144
	v_add_f32_e32 v145, v154, v144
	v_cmp_lt_f32_e32 vcc, s82, v145
	s_cmp_lg_u64 vcc, 0
	v_mov_b32_e32 v144, 1.0
	s_cselect_b64 s[48:49], -1, 0
	v_mov_b32_e32 v146, 1.0
	s_cbranch_vccz .LBB0_232
	v_max_f32_e32 v146, v204, v204
	v_max_f32_e32 v155, v203, v203
	v_max_f32_e32 v146, v155, v146
	v_max_f32_e32 v155, v218, v218
	v_max_f32_e32 v156, v207, v207
	v_max_f32_e32 v155, v156, v155
	v_max_f32_e32 v156, v148, v148
	v_max_f32_e32 v157, v147, v147
	v_max_f32_e32 v156, v157, v156
	v_max_f32_e32 v157, v150, v150
	v_max_f32_e32 v158, v149, v149
	v_max_f32_e32 v157, v158, v157
	v_max_f32_e32 v158, v154, v154
	v_max_f32_e32 v159, v153, v153
	v_max_f32_e32 v158, v159, v158
	v_max3_f32 v158, v151, v152, v158
	v_max3_f32 v146, v201, v202, v146
	v_max3_f32 v155, v205, v206, v155
	v_max3_f32 v156, v156, v157, v158
	v_max3_f32 v146, v146, v155, v156
	v_mov_b32_e32 v155, v146
	s_nop 1
	v_permlane32_swap_b32_e32 v146, v155
	v_max_f32_e32 v155, v155, v155
	v_max_f32_e32 v146, v146, v146
	v_max_f32_e32 v146, v146, v155
.LBB0_232:
	v_cvt_pk_bf16_f32 v224, v201, v202
	v_cvt_pk_bf16_f32 v225, v203, v204
	v_cvt_pk_bf16_f32 v226, v205, v206
	v_cvt_pk_bf16_f32 v227, v207, v218
	v_cvt_pk_bf16_f32 v148, v147, v148
	v_cvt_pk_bf16_f32 v149, v149, v150
	v_cvt_pk_bf16_f32 v150, v151, v152
	v_cvt_pk_bf16_f32 v151, v153, v154
	ds_read_b128 v[204:207], v219 offset:32
	ds_read_b128 v[200:203], v200 offset:1568
	v_add_f32_e32 v179, v179, v145
	v_exp_f32_e32 v155, v128
	v_exp_f32_e32 v129, v129
	v_exp_f32_e32 v130, v130
	v_exp_f32_e32 v131, v131
	s_waitcnt lgkmcnt(2)
	v_mfma_f32_32x32x16_bf16 v[80:95], v[228:231], v[224:227], v[80:95]
	v_add_f32_e32 v128, 0, v155
	v_exp_f32_e32 v132, v132
	v_add_f32_e32 v128, v129, v128
	v_exp_f32_e32 v156, v133
	v_mfma_f32_32x32x16_bf16 v[80:95], v[232:235], v[148:151], v[80:95]
	v_add_f32_e32 v128, v130, v128
	v_exp_f32_e32 v157, v134
	v_add_f32_e32 v128, v131, v128
	v_exp_f32_e32 v158, v135
	v_mfma_f32_32x32x16_bf16 v[48:63], v[236:239], v[224:227], v[48:63]
	v_add_f32_e32 v128, v132, v128
	v_exp_f32_e32 v133, v136
	v_add_f32_e32 v128, v156, v128
	v_exp_f32_e32 v134, v137
	v_mfma_f32_32x32x16_bf16 v[48:63], v[240:243], v[148:151], v[48:63]
	v_add_f32_e32 v128, v157, v128
	v_exp_f32_e32 v135, v138
	v_add_f32_e32 v128, v158, v128
	v_exp_f32_e32 v136, v139
	v_mfma_f32_32x32x16_bf16 v[16:31], v[212:215], v[224:227], v[16:31]
	v_add_f32_e32 v128, v133, v128
	v_exp_f32_e32 v137, v140
	v_add_f32_e32 v128, v134, v128
	v_exp_f32_e32 v138, v141
	v_mfma_f32_32x32x16_bf16 v[112:127], v[220:223], v[224:227], v[112:127]
	v_add_f32_e32 v128, v135, v128
	v_exp_f32_e32 v139, v142
	v_add_f32_e32 v128, v136, v128
	v_exp_f32_e32 v140, v143
	s_waitcnt lgkmcnt(1)
	v_mfma_f32_32x32x16_bf16 v[112:127], v[204:207], v[148:151], v[112:127]
	v_add_f32_e32 v128, v137, v128
	v_add_f32_e32 v128, v138, v128
	v_add_f32_e32 v128, v139, v128
	v_add_f32_e32 v128, v140, v128
	s_waitcnt lgkmcnt(0)
	v_mfma_f32_32x32x16_bf16 v[16:31], v[200:203], v[148:151], v[16:31]
	v_cmp_lt_f32_e32 vcc, s82, v128
	s_cmp_lg_u64 vcc, 0
	s_cselect_b64 s[46:47], -1, 0
	s_cbranch_vccz .LBB0_234
	v_max_f32_e32 v141, v131, v131
	v_max_f32_e32 v142, v130, v130
	v_max_f32_e32 v141, v142, v141
	v_max_f32_e32 v142, v158, v158
	v_max_f32_e32 v143, v157, v157
	v_max_f32_e32 v142, v143, v142
	v_max_f32_e32 v143, v134, v134
	v_max_f32_e32 v144, v133, v133
	v_max_f32_e32 v143, v144, v143
	v_max_f32_e32 v144, v136, v136
	v_max_f32_e32 v159, v135, v135
	v_max_f32_e32 v144, v159, v144
	v_max_f32_e32 v159, v140, v140
	v_max_f32_e32 v147, v139, v139
	v_max_f32_e32 v159, v147, v159
	v_max3_f32 v159, v137, v138, v159
	v_max3_f32 v141, v155, v129, v141
	v_max3_f32 v142, v132, v156, v142
	v_max3_f32 v143, v143, v144, v159
	v_max3_f32 v141, v141, v142, v143
	v_mov_b32_e32 v142, v141
	s_nop 1
	v_permlane32_swap_b32_e32 v141, v142
	v_max_f32_e32 v142, v142, v142
	v_max_f32_e32 v141, v141, v141
	v_max_f32_e32 v144, v141, v142

; #define LAS __attribute__((address_space(3)))
; __device__ __forceinline__ void dattn_unit(LAS unsigned char* lds, int b, int h, int qb, const bf16* Q, const bf16* K, const bf16* V, bf16* YB, float lam, const float* subg, float oml, int tid) {
;     ...
;             AT_SOFTMAX(s0, 0, pA0, pB0);
;             AT_SOFTMAX(s1, 1, pA1, pB1);
; #pragma unroll
;             for (int cb = 0; cb < 4; ++cb) { const LAS bf16* vp = Vt + (32 * cb + ql) * 72 + 32 * sub + 4 * hi;
;                 const v2u a0 = *(const LAS v2u*)(vp), a1 = *(const LAS v2u*)(vp + 8), a2 = *(const LAS v2u*)(vp + 16), a3 = *(const LAS v2u*)(vp + 24);
;                 const v4u f0 = {a0.x, a0.y, a1.x, a1.y}, f1 = {a2.x, a2.y, a3.x, a3.y};
;                 o[0][cb] = __builtin_amdgcn_mfma_f32_32x32x16_bf16(__builtin_bit_cast(bf16x8, f0), pA0, o[0][cb], 0, 0, 0);
;                 o[1][cb] = __builtin_amdgcn_mfma_f32_32x32x16_bf16(__builtin_bit_cast(bf16x8, f0), pA1, o[1][cb], 0, 0, 0);
;                 o[0][cb] = __builtin_amdgcn_mfma_f32_32x32x16_bf16(__builtin_bit_cast(bf16x8, f1), pB0, o[0][cb], 0, 0, 0);
;                 o[1][cb] = __builtin_amdgcn_mfma_f32_32x32x16_bf16(__builtin_bit_cast(bf16x8, f1), pB1, o[1][cb], 0, 0, 0); }
.LBB0_241:
	v_add_u32_e32 v221, s38, v193
	v_add_u32_e32 v221, v221, v192
	v_add_u32_e32 v242, 0x5800, v221
	v_add_u32_e32 v243, 0x7800, v221
	ds_read_b128 v[222:225], v242 offset:576
	ds_read_b128 v[226:229], v242 offset:608
	v_add_u32_e32 v242, 0x6800, v221
	ds_read_b128 v[230:233], v242 offset:1088
	ds_read_b128 v[234:237], v242 offset:1120
	ds_read_b128 v[238:241], v243 offset:1600
	v_add_u32_e32 v242, 0x4800, v221
	ds_read_b128 v[212:215], v242 offset:64
	ds_read_b128 v[200:203], v242 offset:96
	v_exp_f32_e32 v199, v144
	v_exp_f32_e32 v204, v145
	v_exp_f32_e32 v205, v146
	v_exp_f32_e32 v206, v147
	v_add_f32_e32 v144, 0, v199
	v_exp_f32_e32 v207, v148
	v_add_f32_e32 v144, v204, v144
	v_exp_f32_e32 v218, v149
	v_add_f32_e32 v144, v205, v144
	v_exp_f32_e32 v219, v150
	v_add_f32_e32 v144, v206, v144
	v_exp_f32_e32 v220, v151
	v_add_f32_e32 v144, v207, v144
	v_exp_f32_e32 v147, v152
	v_add_f32_e32 v144, v218, v144
	v_exp_f32_e32 v148, v153
	v_add_f32_e32 v144, v219, v144
	v_exp_f32_e32 v149, v154
	v_add_f32_e32 v144, v220, v144
	v_exp_f32_e32 v150, v155
	v_add_f32_e32 v144, v147, v144
	v_exp_f32_e32 v151, v156
	v_add_f32_e32 v144, v148, v144
	v_exp_f32_e32 v152, v157
	v_add_f32_e32 v144, v149, v144
	v_exp_f32_e32 v153, v158
	v_add_f32_e32 v144, v150, v144
	v_exp_f32_e32 v154, v159
	v_add_f32_e32 v144, v151, v144
	v_add_f32_e32 v144, v152, v144
	v_add_f32_e32 v144, v153, v144
	v_add_f32_e32 v145, v154, v144
	v_cmp_lt_f32_e32 vcc, s82, v145
	s_cmp_lg_u64 vcc, 0
	v_mov_b32_e32 v144, 1.0
	s_cselect_b64 s[48:49], -1, 0
	v_mov_b32_e32 v146, 1.0
	s_cbranch_vccz .LBB0_243
	v_max_f32_e32 v146, v206, v206
	v_max_f32_e32 v155, v205, v205
	v_max_f32_e32 v146, v155, v146
	v_max_f32_e32 v155, v220, v220
	v_max_f32_e32 v156, v219, v219
	v_max_f32_e32 v155, v156, v155
	v_max_f32_e32 v156, v148, v148
	v_max_f32_e32 v157, v147, v147
	v_max_f32_e32 v156, v157, v156
	v_max_f32_e32 v157, v150, v150
	v_max_f32_e32 v158, v149, v149
	v_max_f32_e32 v157, v158, v157
	v_max_f32_e32 v158, v154, v154
	v_max_f32_e32 v159, v153, v153
	v_max_f32_e32 v158, v159, v158
	v_max3_f32 v158, v151, v152, v158
	v_max3_f32 v146, v199, v204, v146
	v_max3_f32 v155, v207, v218, v155
	v_max3_f32 v156, v156, v157, v158
	v_max3_f32 v146, v146, v155, v156
	v_mov_b32_e32 v155, v146
	s_nop 1
	v_permlane32_swap_b32_e32 v146, v155
	v_max_f32_e32 v155, v155, v155
	v_max_f32_e32 v146, v146, v146
	v_max_f32_e32 v146, v146, v155
.LBB0_243:
	v_cvt_pk_bf16_f32 v205, v205, v206
	v_cvt_pk_bf16_f32 v206, v207, v218
	v_cvt_pk_bf16_f32 v207, v219, v220
	v_cvt_pk_bf16_f32 v204, v199, v204
	v_cvt_pk_bf16_f32 v148, v147, v148
	v_cvt_pk_bf16_f32 v149, v149, v150
	v_cvt_pk_bf16_f32 v150, v151, v152
	v_cvt_pk_bf16_f32 v151, v153, v154
	ds_read_b128 v[218:221], v243 offset:1632
	v_add_f32_e32 v179, v179, v145
	v_exp_f32_e32 v155, v128
	v_exp_f32_e32 v129, v129
	v_exp_f32_e32 v130, v130
	v_exp_f32_e32 v131, v131
	s_waitcnt lgkmcnt(1)
	v_mfma_f32_32x32x16_bf16 v[80:95], v[222:225], v[204:207], v[80:95]
	v_add_f32_e32 v128, 0, v155
	v_exp_f32_e32 v132, v132
	v_add_f32_e32 v128, v129, v128
	v_exp_f32_e32 v156, v133
	v_mfma_f32_32x32x16_bf16 v[80:95], v[226:229], v[148:151], v[80:95]
	v_add_f32_e32 v128, v130, v128
	v_exp_f32_e32 v157, v134
	v_add_f32_e32 v128, v131, v128
	v_exp_f32_e32 v158, v135
	v_mfma_f32_32x32x16_bf16 v[48:63], v[230:233], v[204:207], v[48:63]
	v_add_f32_e32 v128, v132, v128
	v_exp_f32_e32 v133, v136
	v_add_f32_e32 v128, v156, v128
	v_exp_f32_e32 v134, v137
	v_mfma_f32_32x32x16_bf16 v[48:63], v[234:237], v[148:151], v[48:63]
	v_add_f32_e32 v128, v157, v128
	v_exp_f32_e32 v135, v138
	v_add_f32_e32 v128, v158, v128
	v_exp_f32_e32 v136, v139
	v_mfma_f32_32x32x16_bf16 v[16:31], v[238:241], v[204:207], v[16:31]
	v_add_f32_e32 v128, v133, v128
	v_exp_f32_e32 v137, v140
	v_add_f32_e32 v128, v134, v128
	v_exp_f32_e32 v138, v141
	v_mfma_f32_32x32x16_bf16 v[112:127], v[212:215], v[204:207], v[112:127]
	v_add_f32_e32 v128, v135, v128
	v_exp_f32_e32 v139, v142
	v_add_f32_e32 v128, v136, v128
	v_exp_f32_e32 v140, v143
	v_mfma_f32_32x32x16_bf16 v[112:127], v[200:203], v[148:151], v[112:127]
	v_add_f32_e32 v128, v137, v128
	v_add_f32_e32 v128, v138, v128
	v_add_f32_e32 v128, v139, v128
	v_add_f32_e32 v128, v140, v128
	s_waitcnt lgkmcnt(0)
	v_mfma_f32_32x32x16_bf16 v[16:31], v[218:221], v[148:151], v[16:31]
	v_cmp_lt_f32_e32 vcc, s82, v128
	s_cmp_lg_u64 vcc, 0
	s_cselect_b64 s[46:47], -1, 0
	s_cbranch_vccz .LBB0_245
	v_max_f32_e32 v141, v131, v131
	v_max_f32_e32 v142, v130, v130
	v_max_f32_e32 v141, v142, v141
	v_max_f32_e32 v142, v158, v158
	v_max_f32_e32 v143, v157, v157
	v_max_f32_e32 v142, v143, v142
	v_max_f32_e32 v143, v134, v134
	v_max_f32_e32 v144, v133, v133
	v_max_f32_e32 v143, v144, v143
	v_max_f32_e32 v144, v136, v136
	v_max_f32_e32 v159, v135, v135
	v_max_f32_e32 v144, v159, v144
	v_max_f32_e32 v159, v140, v140
	v_max_f32_e32 v147, v139, v139
	v_max_f32_e32 v159, v147, v159
	v_max3_f32 v159, v137, v138, v159
	v_max3_f32 v141, v155, v129, v141
	v_max3_f32 v142, v132, v156, v142
	v_max3_f32 v143, v143, v144, v159
	v_max3_f32 v141, v141, v142, v143
	v_mov_b32_e32 v142, v141
	s_nop 1
	v_permlane32_swap_b32_e32 v141, v142
	v_max_f32_e32 v142, v142, v142
	v_max_f32_e32 v141, v141, v141
	v_max_f32_e32 v144, v141, v142

; __device__ __forceinline__ void dattn_unit(LAS unsigned char* lds, int b, int h, int qb, const bf16* Q, const bf16* K, const bf16* V, bf16* YB, float lam, const float* subg, float oml, int tid) {
;     ...
; #pragma unroll
;         for (int sub = 0; sub < 2; ++sub) {
;             if (kvbase + 32 * sub > qmax) continue;
;             const bool need_bm = kvbase + 32 * sub + 31 + 113 > qmin;
;             LAS bf16x8* qsp = qs; asm volatile("" : "+v"(qsp));
;             f32x16 s0, s1;
; #pragma unroll
;             for (int r = 0; r < 16; ++r) { s0[r] = -mref[0]; s1[r] = -mref[1]; }
;             {
;                 const LAS bf16* kp = Ks + (32 * sub + ql) * 72 + hi * 8;
;                 bf16x8 ka = *(const LAS bf16x8*)kp, kb = *(const LAS bf16x8*)(kp + 64 * 72), qa = qsp[0], qb = qsp[4 * 64];
;                 __builtin_amdgcn_sched_group_barrier(0x100, 4, 0);
; #pragma unroll
;                 for (int ks = 0; ks < 4; ++ks) { bf16x8 ka2 = ka, kb2 = kb, qa2 = qa, qb2 = qb;
;                     if (ks < 3) { ka2 = *(const LAS bf16x8*)(kp + (ks + 1) * 16); kb2 = *(const LAS bf16x8*)(kp + 64 * 72 + (ks + 1) * 16); qa2 = qsp[(ks + 1) * 64]; qb2 = qsp[(4 + ks + 1) * 64];
;                         __builtin_amdgcn_sched_group_barrier(0x100, 4, 0); }
;                     s0 = __builtin_amdgcn_mfma_f32_32x32x16_bf16(ka, qa, s0, 0, 0, 0);
;                     s1 = __builtin_amdgcn_mfma_f32_32x32x16_bf16(kb, qb, s1, 0, 0, 0);
;                     __builtin_amdgcn_sched_group_barrier(0x008, 2, 0);
;                     ka = ka2; kb = kb2; qa = qa2; qb = qb2; }
;             }
;             if (need_bm) { const LAS float* gb = tab + (159 - (q - (kvbase + 32 * sub + 4 * hi)));
; #pragma unroll
;                 for (int r = 0; r < 16; ++r) { const float bv = gb[(r & 3) + 8 * (r >> 2)]; s0[r] += bv; s1[r] += bv; } }
;             bf16x8 pA0, pB0, pA1, pB1; bool trig[2]; float pmx[2] = {1.f, 1.f};
;             AT_SOFTMAX(s0, 0, pA0, pB0);
;             AT_SOFTMAX(s1, 1, pA1, pB1);
; #pragma unroll
;             for (int cb = 0; cb < 4; ++cb) { const LAS bf16* vp = Vt + (32 * cb + ql) * 72 + 32 * sub + 4 * hi;
;                 const v2u a0 = *(const LAS v2u*)(vp), a1 = *(const LAS v2u*)(vp + 8), a2 = *(const LAS v2u*)(vp + 16), a3 = *(const LAS v2u*)(vp + 24);
;                 const v4u f0 = {a0.x, a0.y, a1.x, a1.y}, f1 = {a2.x, a2.y, a3.x, a3.y};
.LBB0_256:
	v_add_u32_e32 v141, s60, v193
	v_add_u32_e32 v141, v141, v192
	v_cvt_pk_bf16_f32 v182, v164, v165
	v_add_u32_e32 v164, 0x5800, v141
	v_cvt_pk_bf16_f32 v184, v168, v169
	v_cvt_pk_bf16_f32 v185, v170, v171
	v_cvt_pk_bf16_f32 v169, v130, v131
	v_cvt_pk_bf16_f32 v170, v132, v156
	v_cvt_pk_bf16_f32 v130, v133, v134
	v_cvt_pk_bf16_f32 v131, v135, v136
	v_cvt_pk_bf16_f32 v132, v137, v138
	ds_read_b128 v[134:137], v164 offset:512
	v_cvt_pk_bf16_f32 v183, v166, v167
	v_cvt_pk_bf16_f32 v168, v155, v129
	v_cvt_pk_bf16_f32 v171, v157, v158
	s_waitcnt lgkmcnt(0)
	v_mfma_f32_32x32x16_bf16 v[80:95], v[134:137], v[182:185], v[80:95]
	v_cvt_pk_bf16_f32 v148, v147, v148
	v_cvt_pk_bf16_f32 v149, v149, v150
	v_cvt_pk_bf16_f32 v150, v151, v152
	v_cvt_pk_bf16_f32 v151, v153, v154
	v_cvt_pk_bf16_f32 v133, v139, v140
	v_add_u32_e32 v165, 0x6800, v141
	v_add_u32_e32 v166, 0x7800, v141
	v_mfma_f32_32x32x16_bf16 v[64:79], v[134:137], v[168:171], v[64:79]
	ds_read_b128 v[134:137], v164 offset:544
	v_add_u32_e32 v163, 0x4800, v141
	ds_read_b128 v[172:175], v163
	ds_read_b128 v[156:159], v163 offset:32
	v_add_f32_e32 v179, v179, v145
	s_andn2_b64 vcc, exec, s[48:49]
	s_waitcnt lgkmcnt(2)
	v_mfma_f32_32x32x16_bf16 v[80:95], v[134:137], v[148:151], v[80:95]
	v_mfma_f32_32x32x16_bf16 v[64:79], v[134:137], v[130:133], v[64:79]
	ds_read_b128 v[134:137], v165 offset:1024
	s_waitcnt lgkmcnt(0)
	v_mfma_f32_32x32x16_bf16 v[48:63], v[134:137], v[182:185], v[48:63]
	v_mfma_f32_32x32x16_bf16 v[32:47], v[134:137], v[168:171], v[32:47]
	ds_read_b128 v[134:137], v165 offset:1056
	s_waitcnt lgkmcnt(0)
	v_mfma_f32_32x32x16_bf16 v[48:63], v[134:137], v[148:151], v[48:63]
	v_mfma_f32_32x32x16_bf16 v[32:47], v[134:137], v[130:133], v[32:47]
	ds_read_b128 v[134:137], v166 offset:1536
	s_waitcnt lgkmcnt(0)
	v_mfma_f32_32x32x16_bf16 v[16:31], v[134:137], v[182:185], v[16:31]
	v_mfma_f32_32x32x16_bf16 v[0:15], v[134:137], v[168:171], v[0:15]
	ds_read_b128 v[134:137], v166 offset:1568
	v_mfma_f32_32x32x16_bf16 v[112:127], v[172:175], v[182:185], v[112:127]
	v_mfma_f32_32x32x16_bf16 v[96:111], v[172:175], v[168:171], v[96:111]
	v_mfma_f32_32x32x16_bf16 v[112:127], v[156:159], v[148:151], v[112:127]
	v_mfma_f32_32x32x16_bf16 v[96:111], v[156:159], v[130:133], v[96:111]
	s_waitcnt lgkmcnt(0)
	v_mfma_f32_32x32x16_bf16 v[16:31], v[134:137], v[148:151], v[16:31]
	v_mfma_f32_32x32x16_bf16 v[0:15], v[134:137], v[130:133], v[0:15]
	s_cbranch_vccnz .LBB0_258
	v_log_f32_e32 v129, v146
	s_nop 0
	v_max_f32_e32 v129, 0, v129
	v_exp_f32_e64 v130, -v129
	v_add_f32_e32 v190, v190, v129
	s_nop 1
	v_pk_mul_f32 v[126:127], v[130:131], v[126:127] op_sel_hi:[0,1]
	v_pk_mul_f32 v[124:125], v[130:131], v[124:125] op_sel_hi:[0,1]
	v_pk_mul_f32 v[122:123], v[130:131], v[122:123] op_sel_hi:[0,1]
	v_pk_mul_f32 v[120:121], v[130:131], v[120:121] op_sel_hi:[0,1]
	v_pk_mul_f32 v[118:119], v[130:131], v[118:119] op_sel_hi:[0,1]
	v_pk_mul_f32 v[116:117], v[130:131], v[116:117] op_sel_hi:[0,1]
	v_pk_mul_f32 v[114:115], v[130:131], v[114:115] op_sel_hi:[0,1]
	v_pk_mul_f32 v[112:113], v[130:131], v[112:113] op_sel_hi:[0,1]
	v_pk_mul_f32 v[94:95], v[130:131], v[94:95] op_sel_hi:[0,1]
	v_pk_mul_f32 v[92:93], v[130:131], v[92:93] op_sel_hi:[0,1]
	v_pk_mul_f32 v[90:91], v[130:131], v[90:91] op_sel_hi:[0,1]
	v_pk_mul_f32 v[88:89], v[130:131], v[88:89] op_sel_hi:[0,1]
	v_pk_mul_f32 v[86:87], v[130:131], v[86:87] op_sel_hi:[0,1]
	v_pk_mul_f32 v[84:85], v[130:131], v[84:85] op_sel_hi:[0,1]
	v_pk_mul_f32 v[82:83], v[130:131], v[82:83] op_sel_hi:[0,1]
	v_pk_mul_f32 v[80:81], v[130:131], v[80:81] op_sel_hi:[0,1]
	v_pk_mul_f32 v[62:63], v[130:131], v[62:63] op_sel_hi:[0,1]
	v_pk_mul_f32 v[60:61], v[130:131], v[60:61] op_sel_hi:[0,1]
	v_pk_mul_f32 v[58:59], v[130:131], v[58:59] op_sel_hi:[0,1]
	v_pk_mul_f32 v[56:57], v[130:131], v[56:57] op_sel_hi:[0,1]
	v_pk_mul_f32 v[54:55], v[130:131], v[54:55] op_sel_hi:[0,1]
	v_pk_mul_f32 v[52:53], v[130:131], v[52:53] op_sel_hi:[0,1]
	v_pk_mul_f32 v[50:51], v[130:131], v[50:51] op_sel_hi:[0,1]
	v_pk_mul_f32 v[48:49], v[130:131], v[48:49] op_sel_hi:[0,1]
	v_pk_mul_f32 v[30:31], v[130:131], v[30:31] op_sel_hi:[0,1]
	v_pk_mul_f32 v[28:29], v[130:131], v[28:29] op_sel_hi:[0,1]
	v_pk_mul_f32 v[26:27], v[130:131], v[26:27] op_sel_hi:[0,1]
	v_pk_mul_f32 v[24:25], v[130:131], v[24:25] op_sel_hi:[0,1]
	v_pk_mul_f32 v[22:23], v[130:131], v[22:23] op_sel_hi:[0,1]
	v_pk_mul_f32 v[20:21], v[130:131], v[20:21] op_sel_hi:[0,1]
	v_pk_mul_f32 v[18:19], v[130:131], v[18:19] op_sel_hi:[0,1]
	v_pk_mul_f32 v[16:17], v[130:131], v[16:17] op_sel_hi:[0,1]
	v_mul_f32_e32 v179, v179, v130

; __device__ __forceinline__ void dattn_unit(LAS unsigned char* lds, int b, int h, int qb, const bf16* Q, const bf16* K, const bf16* V, bf16* YB, float lam, const float* subg, float oml, int tid) {
;     ...
; #pragma unroll
;         for (int sub = 0; sub < 2; ++sub) {
;             if (kvbase + 32 * sub > qmax) continue;
;             const bool need_bm = kvbase + 32 * sub + 31 + 113 > qmin;
;             LAS bf16x8* qsp = qs; asm volatile("" : "+v"(qsp));
;             f32x16 s0, s1;
; #pragma unroll
;             for (int r = 0; r < 16; ++r) { s0[r] = -mref[0]; s1[r] = -mref[1]; }
;             {
;                 const LAS bf16* kp = Ks + (32 * sub + ql) * 72 + hi * 8;
;                 bf16x8 ka = *(const LAS bf16x8*)kp, kb = *(const LAS bf16x8*)(kp + 64 * 72), qa = qsp[0], qb = qsp[4 * 64];
;                 __builtin_amdgcn_sched_group_barrier(0x100, 4, 0);
; #pragma unroll
;                 for (int ks = 0; ks < 4; ++ks) { bf16x8 ka2 = ka, kb2 = kb, qa2 = qa, qb2 = qb;
;                     if (ks < 3) { ka2 = *(const LAS bf16x8*)(kp + (ks + 1) * 16); kb2 = *(const LAS bf16x8*)(kp + 64 * 72 + (ks + 1) * 16); qa2 = qsp[(ks + 1) * 64]; qb2 = qsp[(4 + ks + 1) * 64];
;                         __builtin_amdgcn_sched_group_barrier(0x100, 4, 0); }
;                     s0 = __builtin_amdgcn_mfma_f32_32x32x16_bf16(ka, qa, s0, 0, 0, 0);
;                     s1 = __builtin_amdgcn_mfma_f32_32x32x16_bf16(kb, qb, s1, 0, 0, 0);
;                     __builtin_amdgcn_sched_group_barrier(0x008, 2, 0);
;                     ka = ka2; kb = kb2; qa = qa2; qb = qb2; }
;             }
;             if (need_bm) { const LAS float* gb = tab + (159 - (q - (kvbase + 32 * sub + 4 * hi)));
; #pragma unroll
;                 for (int r = 0; r < 16; ++r) { const float bv = gb[(r & 3) + 8 * (r >> 2)]; s0[r] += bv; s1[r] += bv; } }
;             bf16x8 pA0, pB0, pA1, pB1; bool trig[2]; float pmx[2] = {1.f, 1.f};
;             AT_SOFTMAX(s0, 0, pA0, pB0);
;             AT_SOFTMAX(s1, 1, pA1, pB1);
; #pragma unroll
;             for (int cb = 0; cb < 4; ++cb) { const LAS bf16* vp = Vt + (32 * cb + ql) * 72 + 32 * sub + 4 * hi;
;                 const v2u a0 = *(const LAS v2u*)(vp), a1 = *(const LAS v2u*)(vp + 8), a2 = *(const LAS v2u*)(vp + 16), a3 = *(const LAS v2u*)(vp + 24);
;                 const v4u f0 = {a0.x, a0.y, a1.x, a1.y}, f1 = {a2.x, a2.y, a3.x, a3.y};
.LBB0_267:
	v_cvt_pk_bf16_f32 v192, v169, v170
	v_cvt_pk_bf16_f32 v169, v130, v131
	v_cvt_pk_bf16_f32 v170, v132, v156
	v_cvt_pk_bf16_f32 v130, v133, v134
	v_cvt_pk_bf16_f32 v131, v135, v136
	v_cvt_pk_bf16_f32 v132, v137, v138
	ds_read_b128 v[134:137], v164 offset:576
	v_cvt_pk_bf16_f32 v190, v161, v162
	v_cvt_pk_bf16_f32 v191, v167, v168
	v_cvt_pk_bf16_f32 v193, v171, v172
	v_cvt_pk_bf16_f32 v168, v155, v129
	v_cvt_pk_bf16_f32 v171, v157, v158
	s_waitcnt lgkmcnt(0)
	v_mfma_f32_32x32x16_bf16 v[80:95], v[134:137], v[190:193], v[80:95]
	v_cvt_pk_bf16_f32 v148, v147, v148
	v_cvt_pk_bf16_f32 v149, v149, v150
	v_cvt_pk_bf16_f32 v150, v151, v152
	v_cvt_pk_bf16_f32 v151, v153, v154
	v_cvt_pk_bf16_f32 v133, v139, v140
	ds_read_b128 v[182:185], v163 offset:64
	ds_read_b128 v[156:159], v163 offset:96
	v_mfma_f32_32x32x16_bf16 v[64:79], v[134:137], v[168:171], v[64:79]
	ds_read_b128 v[134:137], v164 offset:608
	v_add_f32_e32 v179, v179, v145
	s_andn2_b64 vcc, exec, s[48:49]
	s_waitcnt lgkmcnt(0)
	v_mfma_f32_32x32x16_bf16 v[80:95], v[134:137], v[148:151], v[80:95]
	v_mfma_f32_32x32x16_bf16 v[64:79], v[134:137], v[130:133], v[64:79]
	ds_read_b128 v[134:137], v165 offset:1088
	s_waitcnt lgkmcnt(0)
	v_mfma_f32_32x32x16_bf16 v[48:63], v[134:137], v[190:193], v[48:63]
	v_mfma_f32_32x32x16_bf16 v[32:47], v[134:137], v[168:171], v[32:47]
	ds_read_b128 v[134:137], v165 offset:1120
	s_waitcnt lgkmcnt(0)
	v_mfma_f32_32x32x16_bf16 v[48:63], v[134:137], v[148:151], v[48:63]
	v_mfma_f32_32x32x16_bf16 v[32:47], v[134:137], v[130:133], v[32:47]
	ds_read_b128 v[134:137], v166 offset:1600
	s_waitcnt lgkmcnt(0)
	v_mfma_f32_32x32x16_bf16 v[16:31], v[134:137], v[190:193], v[16:31]
	v_mfma_f32_32x32x16_bf16 v[0:15], v[134:137], v[168:171], v[0:15]
	ds_read_b128 v[134:137], v166 offset:1632
	v_mfma_f32_32x32x16_bf16 v[112:127], v[182:185], v[190:193], v[112:127]
	v_mfma_f32_32x32x16_bf16 v[96:111], v[182:185], v[168:171], v[96:111]
	v_mfma_f32_32x32x16_bf16 v[112:127], v[156:159], v[148:151], v[112:127]
	v_mfma_f32_32x32x16_bf16 v[96:111], v[156:159], v[130:133], v[96:111]
	s_waitcnt lgkmcnt(0)
	v_mfma_f32_32x32x16_bf16 v[16:31], v[134:137], v[148:151], v[16:31]
	v_mfma_f32_32x32x16_bf16 v[0:15], v[134:137], v[130:133], v[0:15]
	s_cbranch_vccnz .LBB0_269
	v_log_f32_e32 v129, v146
	s_nop 0
	v_max_f32_e32 v129, 0, v129
	v_exp_f32_e64 v130, -v129
	s_nop 2
	v_pk_mul_f32 v[126:127], v[130:131], v[126:127] op_sel_hi:[0,1]
	v_pk_mul_f32 v[124:125], v[130:131], v[124:125] op_sel_hi:[0,1]
	v_pk_mul_f32 v[122:123], v[130:131], v[122:123] op_sel_hi:[0,1]
	v_pk_mul_f32 v[120:121], v[130:131], v[120:121] op_sel_hi:[0,1]
	v_pk_mul_f32 v[118:119], v[130:131], v[118:119] op_sel_hi:[0,1]
	v_pk_mul_f32 v[116:117], v[130:131], v[116:117] op_sel_hi:[0,1]
	v_pk_mul_f32 v[114:115], v[130:131], v[114:115] op_sel_hi:[0,1]
	v_pk_mul_f32 v[112:113], v[130:131], v[112:113] op_sel_hi:[0,1]
	v_pk_mul_f32 v[94:95], v[130:131], v[94:95] op_sel_hi:[0,1]
	v_pk_mul_f32 v[92:93], v[130:131], v[92:93] op_sel_hi:[0,1]
	v_pk_mul_f32 v[90:91], v[130:131], v[90:91] op_sel_hi:[0,1]
	v_pk_mul_f32 v[88:89], v[130:131], v[88:89] op_sel_hi:[0,1]
	v_pk_mul_f32 v[86:87], v[130:131], v[86:87] op_sel_hi:[0,1]
	v_pk_mul_f32 v[84:85], v[130:131], v[84:85] op_sel_hi:[0,1]
	v_pk_mul_f32 v[82:83], v[130:131], v[82:83] op_sel_hi:[0,1]
	v_pk_mul_f32 v[80:81], v[130:131], v[80:81] op_sel_hi:[0,1]
	v_pk_mul_f32 v[62:63], v[130:131], v[62:63] op_sel_hi:[0,1]
	v_pk_mul_f32 v[60:61], v[130:131], v[60:61] op_sel_hi:[0,1]
	v_pk_mul_f32 v[58:59], v[130:131], v[58:59] op_sel_hi:[0,1]
	v_pk_mul_f32 v[56:57], v[130:131], v[56:57] op_sel_hi:[0,1]
	v_pk_mul_f32 v[54:55], v[130:131], v[54:55] op_sel_hi:[0,1]
	v_pk_mul_f32 v[52:53], v[130:131], v[52:53] op_sel_hi:[0,1]
	v_pk_mul_f32 v[50:51], v[130:131], v[50:51] op_sel_hi:[0,1]
	v_pk_mul_f32 v[48:49], v[130:131], v[48:49] op_sel_hi:[0,1]
	v_pk_mul_f32 v[30:31], v[130:131], v[30:31] op_sel_hi:[0,1]
	v_pk_mul_f32 v[28:29], v[130:131], v[28:29] op_sel_hi:[0,1]
	v_pk_mul_f32 v[26:27], v[130:131], v[26:27] op_sel_hi:[0,1]
	v_pk_mul_f32 v[24:25], v[130:131], v[24:25] op_sel_hi:[0,1]
	v_pk_mul_f32 v[22:23], v[130:131], v[22:23] op_sel_hi:[0,1]
	v_pk_mul_f32 v[20:21], v[130:131], v[20:21] op_sel_hi:[0,1]
	v_pk_mul_f32 v[18:19], v[130:131], v[18:19] op_sel_hi:[0,1]
	v_pk_mul_f32 v[16:17], v[130:131], v[16:17] op_sel_hi:[0,1]
	v_mul_f32_e32 v179, v179, v130
